# mem_qblock prompt loop: next q-block q+ssq loads prefetched during current q-block; QK software-pipelined
# speedup vs baseline: 1.0090x; 1.0046x over previous
.LBB0_1057:
	s_andn2_b64 vcc, exec, s[26:27]
	s_cbranch_vccnz .LBB0_1051
	s_ashr_i32 s26, s31, 5
	s_lshl_b32 s27, s26, 8
	s_bfe_u32 s33, s31, 0x20003
	v_or_b32_e32 v0, s27, v108
	v_or_b32_e32 v8, s27, v125
	v_or_b32_e32 v16, s27, v113
	v_or_b32_e32 v24, s27, v127
	v_or_b32_e32 v32, s27, v116
	s_lshl_b32 s2, s33, 8
	v_ashrrev_i32_e32 v1, 31, v0
	v_ashrrev_i32_e32 v9, 31, v8
	v_ashrrev_i32_e32 v17, 31, v16
	v_ashrrev_i32_e32 v25, 31, v24
	v_ashrrev_i32_e32 v33, 31, v32
	v_or_b32_e32 v54, s27, v129
	v_or_b32_e32 v62, s27, v119
	v_lshlrev_b64 v[0:1], 10, v[0:1]
	v_lshl_or_b32 v40, v107, 1, s2
	v_lshlrev_b64 v[8:9], 10, v[8:9]
	v_lshlrev_b64 v[16:17], 10, v[16:17]
	v_lshlrev_b64 v[24:25], 10, v[24:25]
	v_lshlrev_b64 v[32:33], 10, v[32:33]
	v_ashrrev_i32_e32 v55, 31, v54
	v_ashrrev_i32_e32 v63, 31, v62
	v_add_u32_e32 v70, s27, v131
	v_or_b32_e32 v0, v0, v40
	v_or_b32_e32 v8, v8, v40
	v_or_b32_e32 v16, v16, v40
	v_or_b32_e32 v24, v24, v40
	v_or_b32_e32 v32, v32, v40
	v_lshlrev_b64 v[54:55], 10, v[54:55]
	v_lshlrev_b64 v[62:63], 10, v[62:63]
	v_ashrrev_i32_e32 v71, 31, v70
	v_lshl_add_u64 v[2:3], s[14:15], 0, v[0:1]
	v_lshl_add_u64 v[4:5], s[16:17], 0, v[0:1]
	v_lshl_add_u64 v[10:11], s[14:15], 0, v[8:9]
	v_lshl_add_u64 v[12:13], s[16:17], 0, v[8:9]
	v_lshl_add_u64 v[18:19], s[14:15], 0, v[16:17]
	v_lshl_add_u64 v[20:21], s[16:17], 0, v[16:17]
	v_lshl_add_u64 v[26:27], s[14:15], 0, v[24:25]
	v_lshl_add_u64 v[28:29], s[16:17], 0, v[24:25]
	v_lshl_add_u64 v[34:35], s[14:15], 0, v[32:33]
	v_lshl_add_u64 v[36:37], s[16:17], 0, v[32:33]
	v_or_b32_e32 v54, v54, v40
	v_or_b32_e32 v62, v62, v40
	v_lshlrev_b64 v[74:75], 10, v[70:71]
	s_barrier
	global_load_dwordx4 v[0:3], v[2:3], off
	s_nop 0
	global_load_dwordx4 v[4:7], v[4:5], off
	s_nop 0
	global_load_dwordx4 v[8:11], v[10:11], off
	s_nop 0
	global_load_dwordx4 v[12:15], v[12:13], off
	s_nop 0
	global_load_dwordx4 v[16:19], v[18:19], off
	s_nop 0
	global_load_dwordx4 v[20:23], v[20:21], off
	s_nop 0
	global_load_dwordx4 v[24:27], v[26:27], off
	s_nop 0
	global_load_dwordx4 v[28:31], v[28:29], off
	s_nop 0
	global_load_dwordx4 v[32:35], v[34:35], off
	s_nop 0
	global_load_dwordx4 v[36:39], v[36:37], off
	v_lshl_add_u64 v[56:57], s[14:15], 0, v[54:55]
	v_lshl_add_u64 v[58:59], s[16:17], 0, v[54:55]
	v_lshl_add_u64 v[64:65], s[14:15], 0, v[62:63]
	v_lshl_add_u64 v[66:67], s[16:17], 0, v[62:63]
	v_or_b32_e32 v74, v74, v40
	global_load_dwordx4 v[54:57], v[56:57], off
	s_nop 0
	global_load_dwordx4 v[58:61], v[58:59], off
	s_nop 0
	global_load_dwordx4 v[62:65], v[64:65], off
	s_nop 0
	global_load_dwordx4 v[66:69], v[66:67], off
	v_lshl_add_u64 v[70:71], s[14:15], 0, v[74:75]
	global_load_dwordx4 v[70:73], v[70:71], off
	v_lshl_add_u64 v[74:75], s[16:17], 0, v[74:75]
	global_load_dwordx4 v[74:77], v[74:75], off
	v_add_u32_e32 v51, v109, v126
	v_add_u32_e32 v53, v110, v126
	v_add_u32_e32 v78, v109, v128
	v_add_u32_e32 v79, v110, v128
	v_add_u32_e32 v80, v109, v130
	s_and_b32 s27, s28, 0xe00
	v_or_b32_e32 v40, s27, v106
	s_ashr_i32 s27, s26, 31
	s_lshl_b64 s[26:27], s[26:27], 12
	s_waitcnt vmcnt(15)
	ds_write_b128 v134, v[0:3]
	s_waitcnt vmcnt(14)
	ds_write_b128 v135, v[4:7]
	s_waitcnt vmcnt(13)
	ds_write_b128 v51, v[8:11]
	s_waitcnt vmcnt(12)
	ds_write_b128 v53, v[12:15]
	s_waitcnt vmcnt(11)
	ds_write_b128 v134, v[16:19] offset:17408
	s_waitcnt vmcnt(10)
	ds_write_b128 v135, v[20:23] offset:17408
	s_waitcnt vmcnt(9)
	ds_write_b128 v78, v[24:27]
	s_waitcnt vmcnt(8)
	ds_write_b128 v79, v[28:31]
	s_waitcnt vmcnt(7)
	ds_write_b128 v134, v[32:35] offset:34816
	s_waitcnt vmcnt(6)
	ds_write_b128 v135, v[36:39] offset:34816
	s_waitcnt vmcnt(5)
	ds_write_b128 v80, v[54:57]
	v_add_u32_e32 v0, v110, v130
	s_waitcnt vmcnt(4)
	ds_write_b128 v0, v[58:61]
	s_waitcnt vmcnt(3)
	ds_write_b128 v134, v[62:65] offset:52224
	s_waitcnt vmcnt(2)
	ds_write_b128 v135, v[66:69] offset:52224
	v_add_u32_e32 v0, v109, v132
	s_waitcnt vmcnt(1)
	ds_write_b128 v0, v[70:73]
	v_add_u32_e32 v0, v110, v132
	v_and_b32_e32 v1, 64, v137
	s_waitcnt vmcnt(0)
	ds_write_b128 v0, v[74:77]
	v_xor_b32_e32 v0, 16, v137
	v_add_u32_e32 v1, 64, v1
	v_cmp_lt_i32_e32 vcc, v0, v1
	s_waitcnt lgkmcnt(0)
	s_barrier
	v_cndmask_b32_e32 v0, v137, v0, vcc
	v_lshlrev_b32_e32 v51, 2, v0
	v_xor_b32_e32 v0, 32, v137
	v_cmp_lt_i32_e32 vcc, v0, v1
	s_nop 1
	v_cndmask_b32_e32 v0, v137, v0, vcc
	v_lshlrev_b32_e32 v53, 2, v0
	v_lshl_add_u64 v[0:1], v[44:45], 0, s[26:27]
	v_lshl_add_u64 v[0:1], v[0:1], 0, v[40:41]
	v_lshlrev_b64 v[2:3], 2, v[0:1]
	v_lshlrev_b64 v[0:1], 10, v[0:1]
	v_mad_u64_u32 v[16:17], s[26:27], s33, v138, v[2:3]
	v_lshl_add_u64 v[2:3], v[46:47], 0, v[0:1]
	v_lshl_add_u64 v[0:1], v[48:49], 0, v[0:1]
	v_lshl_add_u64 v[18:19], v[2:3], 0, s[2:3]
	v_lshl_add_u64 v[20:21], v[0:1], 0, s[2:3]
	s_mov_b32 s2, 4
	v_lshl_add_u64 v[220:221], s[22:23], 0, v[20:21]
	global_load_dwordx4 v[232:235], v[220:221], off offset:-128 nt
	global_load_dwordx4 v[236:239], v[220:221], off offset:-64 nt
	global_load_dwordx4 v[240:243], v[220:221], off nt
	global_load_dwordx4 v[248:251], v[220:221], off offset:64 nt
	v_lshl_add_u64 v[222:223], s[22:23], 0, v[16:17]
	v_add_co_u32_e32 v254, vcc, 0x18fc4000, v222
	s_nop 1
	v_addc_co_u32_e32 v255, vcc, 0, v223, vcc
	global_load_dword v252, v[254:255], off
	v_add_co_u32_e32 v254, vcc, 0x18fe5000, v222
	s_nop 1
	v_addc_co_u32_e32 v255, vcc, 0, v223, vcc
	global_load_dword v253, v[254:255], off
.LBB0_1059:
	s_cmp_eq_u32 s2, 4
	s_cbranch_scc0 .Lmq_notfirst
	s_waitcnt vmcnt(0)
	s_branch .Lmq_go
.Lmq_notfirst:
	s_waitcnt vmcnt(8)
.Lmq_go:
	v_mov_b32_e32 v4, v232
	v_mov_b32_e32 v5, v233
	v_mov_b32_e32 v6, v234
	v_mov_b32_e32 v7, v235
	v_mov_b32_e32 v0, v236
	v_mov_b32_e32 v1, v237
	v_mov_b32_e32 v2, v238
	v_mov_b32_e32 v3, v239
	v_mov_b32_e32 v8, v240
	v_mov_b32_e32 v9, v241
	v_mov_b32_e32 v10, v242
	v_mov_b32_e32 v11, v243
	v_mov_b32_e32 v12, v248
	v_mov_b32_e32 v13, v249
	v_mov_b32_e32 v14, v250
	v_mov_b32_e32 v15, v251
	v_mov_b32_e32 v38, v252
	v_mov_b32_e32 v39, v253
	s_cmp_eq_u32 s2, 1
	s_cbranch_scc1 .Lmq_nopf
	v_lshl_add_u64 v[220:221], v[20:21], 0, s[24:25]
	v_lshl_add_u64 v[220:221], s[22:23], 0, v[220:221]
	global_load_dwordx4 v[232:235], v[220:221], off offset:-128 nt
	global_load_dwordx4 v[236:239], v[220:221], off offset:-64 nt
	global_load_dwordx4 v[240:243], v[220:221], off nt
	global_load_dwordx4 v[248:251], v[220:221], off offset:64 nt
	v_lshl_add_u64 v[222:223], v[16:17], 0, s[18:19]
	v_lshl_add_u64 v[222:223], s[22:23], 0, v[222:223]
	v_add_co_u32_e32 v254, vcc, 0x18fc4000, v222
	s_nop 1
	v_addc_co_u32_e32 v255, vcc, 0, v223, vcc
	global_load_dword v252, v[254:255], off
	v_add_co_u32_e32 v254, vcc, 0x18fe5000, v222
	s_nop 1
	v_addc_co_u32_e32 v255, vcc, 0, v223, vcc
	global_load_dword v253, v[254:255], off
.Lmq_nopf:
	ds_read_b128 v[160:163], v123
	ds_read_b128 v[164:167], v123 offset:64
	ds_read_b128 v[168:171], v123 offset:128
	ds_read_b128 v[172:175], v123 offset:192
	ds_read_b128 v[176:179], v123 offset:4352
	ds_read_b128 v[180:183], v123 offset:4416
	ds_read_b128 v[184:187], v123 offset:4480
	ds_read_b128 v[188:191], v123 offset:4544
	v_add_f32_e32 v38, v38, v39
	v_fmamk_f32 v38, v38, 0x3c000000, v136
	v_rsq_f32_e32 v34, v38
	s_nop 0
	v_mul_f32_e32 v40, 0x3e0293ee, v34
	ds_read_b128 v[204:207], v123 offset:8704
	ds_read_b128 v[208:211], v123 offset:8768
	ds_read_b128 v[212:215], v123 offset:8832
	ds_read_b128 v[216:219], v123 offset:8896
	s_waitcnt lgkmcnt(8)
	v_mfma_f32_16x16x32_bf16 v[224:227], v[160:163], v[4:7], 0
	v_mfma_f32_16x16x32_bf16 v[224:227], v[164:167], v[0:3], v[224:227]
	v_mfma_f32_16x16x32_bf16 v[224:227], v[168:171], v[8:11], v[224:227]
	v_mfma_f32_16x16x32_bf16 v[224:227], v[172:175], v[12:15], v[224:227]
	ds_read_b128 v[160:163], v123 offset:13056
	ds_read_b128 v[164:167], v123 offset:13120
	ds_read_b128 v[168:171], v123 offset:13184
	ds_read_b128 v[172:175], v123 offset:13248
	s_waitcnt lgkmcnt(8)
	v_mfma_f32_16x16x32_bf16 v[228:231], v[176:179], v[4:7], 0
	v_mfma_f32_16x16x32_bf16 v[228:231], v[180:183], v[0:3], v[228:231]
	v_mfma_f32_16x16x32_bf16 v[228:231], v[184:187], v[8:11], v[228:231]
	v_mfma_f32_16x16x32_bf16 v[228:231], v[188:191], v[12:15], v[228:231]
	s_nop 3
	v_mul_f32_e32 v36, v40, v224
	v_mul_f32_e32 v37, v40, v225
	v_mul_f32_e32 v28, v40, v226
	v_mul_f32_e32 v29, v40, v227
	ds_read_b128 v[176:179], v123 offset:17408
	ds_read_b128 v[180:183], v123 offset:17472
	ds_read_b128 v[184:187], v123 offset:17536
	ds_read_b128 v[188:191], v123 offset:17600
	s_waitcnt lgkmcnt(8)
	v_mfma_f32_16x16x32_bf16 v[224:227], v[204:207], v[4:7], 0
	v_mfma_f32_16x16x32_bf16 v[224:227], v[208:211], v[0:3], v[224:227]
	v_mfma_f32_16x16x32_bf16 v[224:227], v[212:215], v[8:11], v[224:227]
	v_mfma_f32_16x16x32_bf16 v[224:227], v[216:219], v[12:15], v[224:227]
	s_nop 3
	v_mul_f32_e32 v26, v40, v228
	v_mul_f32_e32 v27, v40, v229
	v_mul_f32_e32 v22, v40, v230
	v_mul_f32_e32 v23, v40, v231
	ds_read_b128 v[204:207], v123 offset:21760
	ds_read_b128 v[208:211], v123 offset:21824
	ds_read_b128 v[212:215], v123 offset:21888
	ds_read_b128 v[216:219], v123 offset:21952
	s_waitcnt lgkmcnt(8)
	v_mfma_f32_16x16x32_bf16 v[228:231], v[160:163], v[4:7], 0
	v_mfma_f32_16x16x32_bf16 v[228:231], v[164:167], v[0:3], v[228:231]
	v_mfma_f32_16x16x32_bf16 v[228:231], v[168:171], v[8:11], v[228:231]
	v_mfma_f32_16x16x32_bf16 v[228:231], v[172:175], v[12:15], v[228:231]
	s_nop 3
	v_mul_f32_e32 v58, v40, v224
	v_mul_f32_e32 v59, v40, v225
	v_mul_f32_e32 v34, v40, v226
	v_mul_f32_e32 v35, v40, v227
	ds_read_b128 v[160:163], v123 offset:26112
	ds_read_b128 v[164:167], v123 offset:26176
	ds_read_b128 v[168:171], v123 offset:26240
	ds_read_b128 v[172:175], v123 offset:26304
	s_waitcnt lgkmcnt(8)
	v_mfma_f32_16x16x32_bf16 v[224:227], v[176:179], v[4:7], 0
	v_mfma_f32_16x16x32_bf16 v[224:227], v[180:183], v[0:3], v[224:227]
	v_mfma_f32_16x16x32_bf16 v[224:227], v[184:187], v[8:11], v[224:227]
	v_mfma_f32_16x16x32_bf16 v[224:227], v[188:191], v[12:15], v[224:227]
	s_nop 3
	v_mul_f32_e32 v32, v40, v228
	v_mul_f32_e32 v33, v40, v229
	v_mul_f32_e32 v24, v40, v230
	v_mul_f32_e32 v25, v40, v231
	ds_read_b128 v[176:179], v123 offset:30464
	ds_read_b128 v[180:183], v123 offset:30528
	ds_read_b128 v[184:187], v123 offset:30592
	ds_read_b128 v[188:191], v123 offset:30656
	s_waitcnt lgkmcnt(8)
	v_mfma_f32_16x16x32_bf16 v[228:231], v[204:207], v[4:7], 0
	v_mfma_f32_16x16x32_bf16 v[228:231], v[208:211], v[0:3], v[228:231]
	v_mfma_f32_16x16x32_bf16 v[228:231], v[212:215], v[8:11], v[228:231]
	v_mfma_f32_16x16x32_bf16 v[228:231], v[216:219], v[12:15], v[228:231]
	s_nop 3
	v_mul_f32_e32 v62, v40, v224
	v_mul_f32_e32 v63, v40, v225
	v_mul_f32_e32 v56, v40, v226
	v_mul_f32_e32 v57, v40, v227
	ds_read_b128 v[204:207], v123 offset:34816
	ds_read_b128 v[208:211], v123 offset:34880
	ds_read_b128 v[212:215], v123 offset:34944
	ds_read_b128 v[216:219], v123 offset:35008
	s_waitcnt lgkmcnt(8)
	v_mfma_f32_16x16x32_bf16 v[224:227], v[160:163], v[4:7], 0
	v_mfma_f32_16x16x32_bf16 v[224:227], v[164:167], v[0:3], v[224:227]
	v_mfma_f32_16x16x32_bf16 v[224:227], v[168:171], v[8:11], v[224:227]
	v_mfma_f32_16x16x32_bf16 v[224:227], v[172:175], v[12:15], v[224:227]
	s_nop 3
	v_mul_f32_e32 v54, v40, v228
	v_mul_f32_e32 v55, v40, v229
	v_mul_f32_e32 v30, v40, v230
	v_mul_f32_e32 v31, v40, v231
	ds_read_b128 v[160:163], v123 offset:39168
	ds_read_b128 v[164:167], v123 offset:39232
	ds_read_b128 v[168:171], v123 offset:39296
	ds_read_b128 v[172:175], v123 offset:39360
	s_waitcnt lgkmcnt(8)
	v_mfma_f32_16x16x32_bf16 v[228:231], v[176:179], v[4:7], 0
	v_mfma_f32_16x16x32_bf16 v[228:231], v[180:183], v[0:3], v[228:231]
	v_mfma_f32_16x16x32_bf16 v[228:231], v[184:187], v[8:11], v[228:231]
	v_mfma_f32_16x16x32_bf16 v[228:231], v[188:191], v[12:15], v[228:231]
	s_nop 3
	v_mul_f32_e32 v86, v40, v224
	v_mul_f32_e32 v87, v40, v225
	v_mul_f32_e32 v74, v40, v226
	v_mul_f32_e32 v75, v40, v227
	ds_read_b128 v[176:179], v123 offset:43520
	ds_read_b128 v[180:183], v123 offset:43584
	ds_read_b128 v[184:187], v123 offset:43648
	ds_read_b128 v[188:191], v123 offset:43712
	s_waitcnt lgkmcnt(8)
	v_mfma_f32_16x16x32_bf16 v[224:227], v[204:207], v[4:7], 0
	v_mfma_f32_16x16x32_bf16 v[224:227], v[208:211], v[0:3], v[224:227]
	v_mfma_f32_16x16x32_bf16 v[224:227], v[212:215], v[8:11], v[224:227]
	v_mfma_f32_16x16x32_bf16 v[224:227], v[216:219], v[12:15], v[224:227]
	s_nop 3
	v_mul_f32_e32 v60, v40, v228
	v_mul_f32_e32 v61, v40, v229
	v_mul_f32_e32 v38, v40, v230
	v_mul_f32_e32 v39, v40, v231
	ds_read_b128 v[204:207], v123 offset:47872
	ds_read_b128 v[208:211], v123 offset:47936
	ds_read_b128 v[212:215], v123 offset:48000
	ds_read_b128 v[216:219], v123 offset:48064
	s_waitcnt lgkmcnt(8)
	v_mfma_f32_16x16x32_bf16 v[228:231], v[160:163], v[4:7], 0
	v_mfma_f32_16x16x32_bf16 v[228:231], v[164:167], v[0:3], v[228:231]
	v_mfma_f32_16x16x32_bf16 v[228:231], v[168:171], v[8:11], v[228:231]
	v_mfma_f32_16x16x32_bf16 v[228:231], v[172:175], v[12:15], v[228:231]
	s_nop 3
	v_mul_f32_e32 v94, v40, v224
	v_mul_f32_e32 v95, v40, v225
	v_mul_f32_e32 v84, v40, v226
	v_mul_f32_e32 v85, v40, v227
	ds_read_b128 v[160:163], v123 offset:52224
	ds_read_b128 v[164:167], v123 offset:52288
	ds_read_b128 v[168:171], v123 offset:52352
	ds_read_b128 v[172:175], v123 offset:52416
	s_waitcnt lgkmcnt(8)
	v_mfma_f32_16x16x32_bf16 v[224:227], v[176:179], v[4:7], 0
	v_mfma_f32_16x16x32_bf16 v[224:227], v[180:183], v[0:3], v[224:227]
	v_mfma_f32_16x16x32_bf16 v[224:227], v[184:187], v[8:11], v[224:227]
	v_mfma_f32_16x16x32_bf16 v[224:227], v[188:191], v[12:15], v[224:227]
	s_nop 3
	v_mul_f32_e32 v78, v40, v228
	v_mul_f32_e32 v79, v40, v229
	v_mul_f32_e32 v72, v40, v230
	v_mul_f32_e32 v73, v40, v231
	ds_read_b128 v[176:179], v123 offset:56576
	ds_read_b128 v[180:183], v123 offset:56640
	ds_read_b128 v[184:187], v123 offset:56704
	ds_read_b128 v[188:191], v123 offset:56768
	s_waitcnt lgkmcnt(8)
	v_mfma_f32_16x16x32_bf16 v[228:231], v[204:207], v[4:7], 0
	v_mfma_f32_16x16x32_bf16 v[228:231], v[208:211], v[0:3], v[228:231]
	v_mfma_f32_16x16x32_bf16 v[228:231], v[212:215], v[8:11], v[228:231]
	v_mfma_f32_16x16x32_bf16 v[228:231], v[216:219], v[12:15], v[228:231]
	s_nop 3
	v_mul_f32_e32 v102, v40, v224
	v_mul_f32_e32 v103, v40, v225
	v_mul_f32_e32 v92, v40, v226
	v_mul_f32_e32 v93, v40, v227
	ds_read_b128 v[204:207], v123 offset:60928
	ds_read_b128 v[208:211], v123 offset:60992
	ds_read_b128 v[212:215], v123 offset:61056
	ds_read_b128 v[216:219], v123 offset:61120
	s_waitcnt lgkmcnt(8)
	v_mfma_f32_16x16x32_bf16 v[224:227], v[160:163], v[4:7], 0
	v_mfma_f32_16x16x32_bf16 v[224:227], v[164:167], v[0:3], v[224:227]
	v_mfma_f32_16x16x32_bf16 v[224:227], v[168:171], v[8:11], v[224:227]
	v_mfma_f32_16x16x32_bf16 v[224:227], v[172:175], v[12:15], v[224:227]
	s_nop 3
	v_mul_f32_e32 v90, v40, v228
	v_mul_f32_e32 v91, v40, v229
	v_mul_f32_e32 v76, v40, v230
	v_mul_f32_e32 v77, v40, v231
	ds_read_b128 v[160:163], v123 offset:65280
	ds_read_b128 v[164:167], v123 offset:65344
	ds_read_b128 v[168:171], v123 offset:65408
	ds_read_b128 v[172:175], v123 offset:65472
	s_waitcnt lgkmcnt(8)
	v_mfma_f32_16x16x32_bf16 v[228:231], v[176:179], v[4:7], 0
	v_mfma_f32_16x16x32_bf16 v[228:231], v[180:183], v[0:3], v[228:231]
	v_mfma_f32_16x16x32_bf16 v[228:231], v[184:187], v[8:11], v[228:231]
	v_mfma_f32_16x16x32_bf16 v[228:231], v[188:191], v[12:15], v[228:231]
	s_nop 3
	v_mul_f32_e32 v104, v40, v224
	v_mul_f32_e32 v105, v40, v225
	v_mul_f32_e32 v100, v40, v226
	v_mul_f32_e32 v101, v40, v227
	s_waitcnt lgkmcnt(4)
	v_mfma_f32_16x16x32_bf16 v[224:227], v[204:207], v[4:7], 0
	v_mfma_f32_16x16x32_bf16 v[224:227], v[208:211], v[0:3], v[224:227]
	v_mfma_f32_16x16x32_bf16 v[224:227], v[212:215], v[8:11], v[224:227]
	v_mfma_f32_16x16x32_bf16 v[224:227], v[216:219], v[12:15], v[224:227]
	s_nop 3
	v_mul_f32_e32 v98, v40, v228
	v_mul_f32_e32 v99, v40, v229
	v_mul_f32_e32 v88, v40, v230
	v_mul_f32_e32 v89, v40, v231
	s_waitcnt lgkmcnt(0)
	v_mfma_f32_16x16x32_bf16 v[228:231], v[160:163], v[4:7], 0
	v_mfma_f32_16x16x32_bf16 v[228:231], v[164:167], v[0:3], v[228:231]
	v_mfma_f32_16x16x32_bf16 v[228:231], v[168:171], v[8:11], v[228:231]
	v_mfma_f32_16x16x32_bf16 v[228:231], v[172:175], v[12:15], v[228:231]
	s_nop 3
	v_mul_f32_e32 v0, v40, v224
	v_mul_f32_e32 v1, v40, v225
	v_mul_f32_e32 v4, v40, v226
	v_mul_f32_e32 v5, v40, v227
	s_nop 7
	v_mul_f32_e32 v2, v40, v228
	v_mul_f32_e32 v3, v40, v229
	v_mul_f32_e32 v6, v40, v230
	v_mul_f32_e32 v7, v40, v231
	v_max_f32_e32 v8, v36, v37
	v_max_f32_e32 v9, v28, v29
	v_max3_f32 v8, v8, s30, v9
	v_max_f32_e32 v9, v26, v27
	v_max_f32_e32 v10, v22, v23
	v_max3_f32 v8, v8, v9, v10
	v_max_f32_e32 v9, v58, v59
	v_max_f32_e32 v10, v34, v35
	v_max3_f32 v8, v8, v9, v10
	v_max_f32_e32 v9, v32, v33
	v_max_f32_e32 v10, v24, v25
	v_max3_f32 v8, v8, v9, v10
	v_max_f32_e32 v9, v62, v63
	v_max_f32_e32 v10, v56, v57
	v_max3_f32 v8, v8, v9, v10
	v_max_f32_e32 v9, v54, v55
	v_max_f32_e32 v10, v30, v31
	v_max3_f32 v8, v8, v9, v10
	v_max_f32_e32 v9, v86, v87
	v_max_f32_e32 v10, v74, v75
	v_max3_f32 v8, v8, v9, v10
	v_max_f32_e32 v9, v60, v61
	v_max_f32_e32 v10, v38, v39
	v_max3_f32 v8, v8, v9, v10
	v_max_f32_e32 v9, v94, v95
	v_max_f32_e32 v10, v84, v85
	v_max3_f32 v8, v8, v9, v10
	v_max_f32_e32 v9, v78, v79
	v_max_f32_e32 v10, v72, v73
	v_max3_f32 v8, v8, v9, v10
	v_max_f32_e32 v9, v102, v103
	v_max_f32_e32 v10, v92, v93
	v_max3_f32 v8, v8, v9, v10
	v_max_f32_e32 v9, v90, v91
	v_max_f32_e32 v10, v76, v77
	v_max3_f32 v8, v8, v9, v10
	v_max_f32_e32 v9, v104, v105
	v_max_f32_e32 v10, v100, v101
	v_max3_f32 v8, v8, v9, v10
	v_max_f32_e32 v9, v98, v99
	v_max_f32_e32 v10, v88, v89
	v_max3_f32 v8, v8, v9, v10
	v_max_f32_e32 v9, v0, v1
	v_max_f32_e32 v10, v4, v5
	v_max3_f32 v8, v8, v9, v10
	v_max_f32_e32 v9, v2, v3
	v_max_f32_e32 v10, v6, v7
	v_max3_f32 v8, v8, v9, v10
	ds_bpermute_b32 v9, v51, v8
	s_waitcnt lgkmcnt(0)
	v_max_f32_e32 v9, v9, v9
	v_max_f32_e32 v8, v8, v9
	ds_bpermute_b32 v9, v53, v8
	s_waitcnt lgkmcnt(0)
	v_max_f32_e32 v9, v9, v9
	v_max_f32_e32 v8, v8, v9
	v_sub_f32_e32 v9, v36, v8
	v_exp_f32_e32 v140, v9
	v_sub_f32_e32 v9, v37, v8
	v_exp_f32_e32 v141, v9
	v_sub_f32_e32 v9, v28, v8
	v_exp_f32_e32 v142, v9
	v_sub_f32_e32 v9, v29, v8
	v_exp_f32_e32 v143, v9
	v_sub_f32_e32 v10, v26, v8
	v_add_f32_e32 v9, 0, v140
	v_exp_f32_e32 v144, v10
	v_sub_f32_e32 v10, v27, v8
	v_add_f32_e32 v9, v141, v9
	v_exp_f32_e32 v145, v10
	v_sub_f32_e32 v10, v22, v8
	v_add_f32_e32 v9, v142, v9
	v_exp_f32_e32 v146, v10
	v_sub_f32_e32 v10, v23, v8
	v_add_f32_e32 v9, v143, v9
	v_exp_f32_e32 v147, v10
	v_sub_f32_e32 v10, v58, v8
	v_add_f32_e32 v9, v144, v9
	v_exp_f32_e32 v70, v10
	v_sub_f32_e32 v10, v59, v8
	v_add_f32_e32 v9, v145, v9
	v_exp_f32_e32 v71, v10
	v_sub_f32_e32 v10, v34, v8
	v_add_f32_e32 v9, v146, v9
	v_exp_f32_e32 v82, v10
	v_sub_f32_e32 v10, v35, v8
	v_add_f32_e32 v9, v147, v9
	v_exp_f32_e32 v83, v10
	v_sub_f32_e32 v10, v32, v8
	v_add_f32_e32 v9, v70, v9
	v_exp_f32_e32 v80, v10
	v_sub_f32_e32 v10, v33, v8
	v_add_f32_e32 v9, v71, v9
	v_exp_f32_e32 v81, v10
	v_sub_f32_e32 v10, v24, v8
	v_add_f32_e32 v9, v82, v9
	v_exp_f32_e32 v96, v10
	v_sub_f32_e32 v10, v25, v8
	v_add_f32_e32 v9, v83, v9
	v_exp_f32_e32 v97, v10
	v_sub_f32_e32 v10, v62, v8
	v_add_f32_e32 v9, v80, v9
	v_exp_f32_e32 v62, v10
	v_sub_f32_e32 v10, v63, v8
	v_add_f32_e32 v9, v81, v9
	v_exp_f32_e32 v63, v10
	v_sub_f32_e32 v10, v56, v8
	v_add_f32_e32 v9, v96, v9
	v_exp_f32_e32 v66, v10
	v_sub_f32_e32 v10, v57, v8
	v_add_f32_e32 v9, v97, v9
	v_exp_f32_e32 v67, v10
	v_sub_f32_e32 v10, v54, v8
	v_add_f32_e32 v9, v62, v9
	v_exp_f32_e32 v64, v10
	v_sub_f32_e32 v10, v55, v8
	v_add_f32_e32 v9, v63, v9
	v_exp_f32_e32 v65, v10
	v_sub_f32_e32 v10, v30, v8
	v_add_f32_e32 v9, v66, v9
	v_exp_f32_e32 v68, v10
	v_sub_f32_e32 v10, v31, v8
	v_add_f32_e32 v9, v67, v9
	v_exp_f32_e32 v69, v10
	v_sub_f32_e32 v10, v86, v8
	v_add_f32_e32 v9, v64, v9
	v_exp_f32_e32 v54, v10
	v_sub_f32_e32 v10, v87, v8
	v_add_f32_e32 v9, v65, v9
	v_exp_f32_e32 v55, v10
	v_sub_f32_e32 v10, v74, v8
	v_add_f32_e32 v9, v68, v9
	v_exp_f32_e32 v58, v10
	v_sub_f32_e32 v10, v75, v8
	v_add_f32_e32 v9, v69, v9
	v_exp_f32_e32 v59, v10
	v_sub_f32_e32 v10, v60, v8
	v_add_f32_e32 v9, v54, v9
	v_exp_f32_e32 v56, v10
	v_sub_f32_e32 v10, v61, v8
	v_add_f32_e32 v9, v55, v9
	v_exp_f32_e32 v57, v10
	v_sub_f32_e32 v10, v38, v8
	v_add_f32_e32 v9, v58, v9
	v_exp_f32_e32 v60, v10
	v_sub_f32_e32 v10, v39, v8
	v_add_f32_e32 v9, v59, v9
	v_exp_f32_e32 v61, v10
	v_sub_f32_e32 v10, v94, v8
	v_add_f32_e32 v9, v56, v9
	v_exp_f32_e32 v32, v10
	v_sub_f32_e32 v10, v95, v8
	v_add_f32_e32 v9, v57, v9
	v_exp_f32_e32 v33, v10
	v_sub_f32_e32 v10, v84, v8
	v_add_f32_e32 v9, v60, v9
	v_exp_f32_e32 v36, v10
	v_sub_f32_e32 v10, v85, v8
	v_add_f32_e32 v9, v61, v9
	v_exp_f32_e32 v37, v10
	v_sub_f32_e32 v10, v78, v8
	v_add_f32_e32 v9, v32, v9
	v_exp_f32_e32 v34, v10
	v_sub_f32_e32 v10, v79, v8
	v_add_f32_e32 v9, v33, v9
	v_exp_f32_e32 v35, v10
	v_sub_f32_e32 v10, v72, v8
	v_add_f32_e32 v9, v36, v9
	v_exp_f32_e32 v38, v10
	v_sub_f32_e32 v10, v73, v8
	v_add_f32_e32 v9, v37, v9
	v_exp_f32_e32 v39, v10
	v_sub_f32_e32 v10, v102, v8
	v_add_f32_e32 v9, v34, v9
	v_exp_f32_e32 v24, v10
	v_sub_f32_e32 v10, v103, v8
	v_add_f32_e32 v9, v35, v9
	v_exp_f32_e32 v25, v10
	v_sub_f32_e32 v10, v92, v8
	v_add_f32_e32 v9, v38, v9
	v_exp_f32_e32 v28, v10
	v_sub_f32_e32 v10, v93, v8
	v_add_f32_e32 v9, v39, v9
	v_exp_f32_e32 v29, v10
	v_sub_f32_e32 v10, v90, v8
	v_add_f32_e32 v9, v24, v9
	v_exp_f32_e32 v26, v10
	v_sub_f32_e32 v10, v91, v8
	v_add_f32_e32 v9, v25, v9
	v_exp_f32_e32 v27, v10
	v_sub_f32_e32 v10, v76, v8
	v_add_f32_e32 v9, v28, v9
	v_exp_f32_e32 v30, v10
	v_sub_f32_e32 v10, v77, v8
	v_add_f32_e32 v9, v29, v9
	v_exp_f32_e32 v31, v10
	v_sub_f32_e32 v10, v104, v8
	v_add_f32_e32 v9, v26, v9
	v_exp_f32_e32 v10, v10
	v_sub_f32_e32 v11, v105, v8
	v_add_f32_e32 v9, v27, v9
	v_exp_f32_e32 v11, v11
	v_sub_f32_e32 v12, v100, v8
	v_add_f32_e32 v9, v30, v9
	v_exp_f32_e32 v14, v12
	v_sub_f32_e32 v12, v101, v8
	v_add_f32_e32 v9, v31, v9
	v_exp_f32_e32 v15, v12
	v_sub_f32_e32 v12, v98, v8
	v_add_f32_e32 v9, v10, v9
	v_exp_f32_e32 v12, v12
	v_sub_f32_e32 v13, v99, v8
	v_add_f32_e32 v9, v11, v9
	v_exp_f32_e32 v13, v13
	v_sub_f32_e32 v22, v88, v8
	v_add_f32_e32 v9, v14, v9
	v_exp_f32_e32 v22, v22
	v_sub_f32_e32 v23, v89, v8
	v_add_f32_e32 v9, v15, v9
	v_exp_f32_e32 v23, v23
	v_sub_f32_e32 v0, v0, v8
	v_add_f32_e32 v9, v12, v9
	v_exp_f32_e32 v0, v0
	v_sub_f32_e32 v1, v1, v8
	v_add_f32_e32 v9, v13, v9
	v_exp_f32_e32 v1, v1
	v_sub_f32_e32 v4, v4, v8
	v_add_f32_e32 v9, v22, v9
	v_exp_f32_e32 v4, v4
	v_sub_f32_e32 v5, v5, v8
	v_add_f32_e32 v9, v23, v9
	v_exp_f32_e32 v5, v5
	v_sub_f32_e32 v2, v2, v8
	v_add_f32_e32 v9, v0, v9
	v_exp_f32_e32 v2, v2
	v_sub_f32_e32 v3, v3, v8
	v_add_f32_e32 v9, v1, v9
	v_exp_f32_e32 v3, v3
	v_sub_f32_e32 v6, v6, v8
	v_add_f32_e32 v9, v4, v9
	v_exp_f32_e32 v6, v6
	v_sub_f32_e32 v7, v7, v8
	v_add_f32_e32 v9, v5, v9
	v_exp_f32_e32 v7, v7
	v_add_f32_e32 v8, v2, v9
	v_add_f32_e32 v8, v3, v8
	v_add_f32_e32 v8, v6, v8
	v_add_f32_e32 v8, v7, v8
	ds_bpermute_b32 v9, v51, v8
	ds_read_b64_tr_b16 v[78:79], v133 offset:4352
	ds_read_b64_tr_b16 v[76:77], v133
	s_waitcnt lgkmcnt(2)
	v_add_f32_e32 v8, v8, v9
	ds_bpermute_b32 v9, v53, v8
	s_waitcnt lgkmcnt(0)
	v_add_f32_e32 v8, v8, v9
	v_rcp_f32_e32 v8, v8
	s_nop 0
	v_pk_mul_f32 v[74:75], v[142:143], v[8:9] op_sel_hi:[1,0]
	v_pk_mul_f32 v[72:73], v[140:141], v[8:9] op_sel_hi:[1,0]
	v_pk_mul_f32 v[84:85], v[146:147], v[8:9] op_sel_hi:[1,0]
	v_pk_mul_f32 v[86:87], v[144:145], v[8:9] op_sel_hi:[1,0]
	v_cvt_pk_bf16_f32 v72, v72, v73
	v_cvt_pk_bf16_f32 v73, v74, v75
	v_cvt_pk_bf16_f32 v74, v86, v87
	v_cvt_pk_bf16_f32 v75, v84, v85
	ds_read_b64_tr_b16 v[86:87], v133 offset:4384
	ds_read_b64_tr_b16 v[84:85], v133 offset:32
	ds_read_b64_tr_b16 v[88:89], v133 offset:64
	ds_read_b64_tr_b16 v[92:93], v133 offset:96
	ds_read_b64_tr_b16 v[90:91], v133 offset:4416
	ds_read_b64_tr_b16 v[94:95], v133 offset:4448
	ds_read_b64_tr_b16 v[98:99], v133 offset:128
	ds_read_b64_tr_b16 v[100:101], v133 offset:4480
	ds_read_b64_tr_b16 v[104:105], v133 offset:4512
	ds_read_b64_tr_b16 v[102:103], v133 offset:160
	ds_read_b64_tr_b16 v[140:141], v133 offset:192
	ds_read_b64_tr_b16 v[144:145], v133 offset:224
	ds_read_b64_tr_b16 v[142:143], v133 offset:4544
	ds_read_b64_tr_b16 v[146:147], v133 offset:4576
	v_mfma_f32_16x16x32_bf16 v[76:79], v[76:79], v[72:75], 0
	s_waitcnt lgkmcnt(12)
	v_mfma_f32_16x16x32_bf16 v[84:87], v[84:87], v[72:75], 0
	s_waitcnt lgkmcnt(9)
	v_mfma_f32_16x16x32_bf16 v[88:91], v[88:91], v[72:75], 0
	s_waitcnt lgkmcnt(8)
	v_mfma_f32_16x16x32_bf16 v[92:95], v[92:95], v[72:75], 0
	s_waitcnt lgkmcnt(6)
	v_mfma_f32_16x16x32_bf16 v[98:101], v[98:101], v[72:75], 0
	s_waitcnt lgkmcnt(4)
	v_mfma_f32_16x16x32_bf16 v[102:105], v[102:105], v[72:75], 0
	s_waitcnt lgkmcnt(1)
	v_mfma_f32_16x16x32_bf16 v[140:143], v[140:143], v[72:75], 0
	s_waitcnt lgkmcnt(0)
	v_mfma_f32_16x16x32_bf16 v[72:75], v[144:147], v[72:75], 0
	v_mul_f32_e64 v82, v82, v8
	v_mul_f32_e64 v83, v83, v8
	v_pk_mul_f32 v[148:149], v[80:81], v[8:9] op_sel_hi:[1,0]
	v_cvt_pk_bf16_f32 v81, v82, v83
	ds_read_b64_tr_b16 v[146:147], v133 offset:13056
	ds_read_b64_tr_b16 v[144:145], v133 offset:8704
	v_cvt_pk_bf16_f32 v82, v148, v149
	ds_read_b64_tr_b16 v[150:151], v133 offset:13088
	ds_read_b64_tr_b16 v[148:149], v133 offset:8736
	ds_read_b64_tr_b16 v[152:153], v133 offset:8768
	ds_read_b64_tr_b16 v[156:157], v133 offset:8800
	ds_read_b64_tr_b16 v[154:155], v133 offset:13120
	ds_read_b64_tr_b16 v[158:159], v133 offset:13152
	v_pk_mul_f32 v[70:71], v[70:71], v[8:9] op_sel_hi:[1,0]
	v_pk_mul_f32 v[96:97], v[96:97], v[8:9] op_sel_hi:[1,0]
	v_cvt_pk_bf16_f32 v80, v70, v71
	v_cvt_pk_bf16_f32 v83, v96, v97
	s_waitcnt lgkmcnt(6)
	s_nop 0
	v_mfma_f32_16x16x32_bf16 v[76:79], v[144:147], v[80:83], v[76:79]
	ds_read_b64_tr_b16 v[144:145], v133 offset:8832
	ds_read_b64_tr_b16 v[146:147], v133 offset:13184
	s_waitcnt lgkmcnt(6)
	v_mfma_f32_16x16x32_bf16 v[84:87], v[148:151], v[80:83], v[84:87]
	s_waitcnt lgkmcnt(3)
	v_mfma_f32_16x16x32_bf16 v[88:91], v[152:155], v[80:83], v[88:91]
	s_waitcnt lgkmcnt(2)
	v_mfma_f32_16x16x32_bf16 v[92:95], v[156:159], v[80:83], v[92:95]
	ds_read_b64_tr_b16 v[150:151], v133 offset:13216
	ds_read_b64_tr_b16 v[148:149], v133 offset:8864
	ds_read_b64_tr_b16 v[152:153], v133 offset:8896
	ds_read_b64_tr_b16 v[156:157], v133 offset:8928
	ds_read_b64_tr_b16 v[154:155], v133 offset:13248
	ds_read_b64_tr_b16 v[158:159], v133 offset:13280
	s_waitcnt lgkmcnt(6)
	v_mfma_f32_16x16x32_bf16 v[96:99], v[144:147], v[80:83], v[98:101]
	s_waitcnt lgkmcnt(4)
	v_mfma_f32_16x16x32_bf16 v[100:103], v[148:151], v[80:83], v[102:105]
	s_waitcnt lgkmcnt(1)
	v_mfma_f32_16x16x32_bf16 v[140:143], v[152:155], v[80:83], v[140:143]
	s_waitcnt lgkmcnt(0)
	v_mfma_f32_16x16x32_bf16 v[70:73], v[156:159], v[80:83], v[72:75]
	v_mul_f32_e64 v66, v66, v8
	v_mul_f32_e64 v67, v67, v8
	v_pk_mul_f32 v[62:63], v[62:63], v[8:9] op_sel_hi:[1,0]
	v_pk_mul_f32 v[74:75], v[68:69], v[8:9] op_sel_hi:[1,0]
	v_cvt_pk_bf16_f32 v62, v62, v63
	v_cvt_pk_bf16_f32 v63, v66, v67
	ds_read_b64_tr_b16 v[68:69], v133 offset:21760
	ds_read_b64_tr_b16 v[66:67], v133 offset:17408
	ds_read_b64_tr_b16 v[82:83], v133 offset:21792
	ds_read_b64_tr_b16 v[80:81], v133 offset:17440
	ds_read_b64_tr_b16 v[144:145], v133 offset:17472
	ds_read_b64_tr_b16 v[148:149], v133 offset:17504
	ds_read_b64_tr_b16 v[146:147], v133 offset:21824
	ds_read_b64_tr_b16 v[150:151], v133 offset:21856
	v_pk_mul_f32 v[64:65], v[64:65], v[8:9] op_sel_hi:[1,0]
	s_nop 0
	v_cvt_pk_bf16_f32 v64, v64, v65
	v_cvt_pk_bf16_f32 v65, v74, v75
	s_waitcnt lgkmcnt(6)
	s_nop 0
	v_mfma_f32_16x16x32_bf16 v[66:69], v[66:69], v[62:65], v[76:79]
	s_waitcnt lgkmcnt(4)
	v_mfma_f32_16x16x32_bf16 v[74:77], v[80:83], v[62:65], v[84:87]
	ds_read_b64_tr_b16 v[82:83], v133 offset:17536
	s_nop 1
	ds_read_b64_tr_b16 v[84:85], v133 offset:21888
	s_waitcnt lgkmcnt(3)
	v_mfma_f32_16x16x32_bf16 v[78:81], v[144:147], v[62:65], v[88:91]
	s_waitcnt lgkmcnt(2)
	v_mfma_f32_16x16x32_bf16 v[86:89], v[148:151], v[62:65], v[92:95]
	s_nop 2
	ds_read_b64_tr_b16 v[92:93], v133 offset:21920
	ds_read_b64_tr_b16 v[90:91], v133 offset:17568
	ds_read_b64_tr_b16 v[144:145], v133 offset:17600
	ds_read_b64_tr_b16 v[148:149], v133 offset:17632
	ds_read_b64_tr_b16 v[146:147], v133 offset:21952
	ds_read_b64_tr_b16 v[150:151], v133 offset:21984
	s_waitcnt lgkmcnt(6)
	v_mfma_f32_16x16x32_bf16 v[82:85], v[82:85], v[62:65], v[96:99]
	s_waitcnt lgkmcnt(4)
	v_mfma_f32_16x16x32_bf16 v[90:93], v[90:93], v[62:65], v[100:103]
	s_waitcnt lgkmcnt(1)
	v_mfma_f32_16x16x32_bf16 v[94:97], v[144:147], v[62:65], v[140:143]
	s_waitcnt lgkmcnt(0)
	v_mfma_f32_16x16x32_bf16 v[62:65], v[148:151], v[62:65], v[70:73]
	v_mul_f32_e64 v58, v58, v8
	v_mul_f32_e64 v59, v59, v8
	v_pk_mul_f32 v[54:55], v[54:55], v[8:9] op_sel_hi:[1,0]
	v_pk_mul_f32 v[70:71], v[60:61], v[8:9] op_sel_hi:[1,0]
	v_pk_mul_f32 v[56:57], v[56:57], v[8:9] op_sel_hi:[1,0]
	v_cvt_pk_bf16_f32 v54, v54, v55
	v_cvt_pk_bf16_f32 v55, v58, v59
	ds_read_b64_tr_b16 v[60:61], v133 offset:30464
	ds_read_b64_tr_b16 v[58:59], v133 offset:26112
	v_cvt_pk_bf16_f32 v56, v56, v57
	v_cvt_pk_bf16_f32 v57, v70, v71
	ds_read_b64_tr_b16 v[72:73], v133 offset:30496
	ds_read_b64_tr_b16 v[70:71], v133 offset:26144
	ds_read_b64_tr_b16 v[98:99], v133 offset:26176
	ds_read_b64_tr_b16 v[102:103], v133 offset:26208
	ds_read_b64_tr_b16 v[100:101], v133 offset:30528
	ds_read_b64_tr_b16 v[104:105], v133 offset:30560
	s_waitcnt lgkmcnt(6)
	v_mfma_f32_16x16x32_bf16 v[58:61], v[58:61], v[54:57], v[66:69]
	s_waitcnt lgkmcnt(4)
	v_mfma_f32_16x16x32_bf16 v[66:69], v[70:73], v[54:57], v[74:77]
	s_nop 2
	ds_read_b64_tr_b16 v[74:75], v133 offset:26240
	ds_read_b64_tr_b16 v[76:77], v133 offset:30592
	s_waitcnt lgkmcnt(3)
	v_mfma_f32_16x16x32_bf16 v[70:73], v[98:101], v[54:57], v[78:81]
	s_waitcnt lgkmcnt(2)
	v_mfma_f32_16x16x32_bf16 v[78:81], v[102:105], v[54:57], v[86:89]
	s_nop 2
	ds_read_b64_tr_b16 v[88:89], v133 offset:30624
	ds_read_b64_tr_b16 v[86:87], v133 offset:26272
	ds_read_b64_tr_b16 v[98:99], v133 offset:26304
	ds_read_b64_tr_b16 v[102:103], v133 offset:26336
	ds_read_b64_tr_b16 v[100:101], v133 offset:30656
	ds_read_b64_tr_b16 v[104:105], v133 offset:30688
	s_waitcnt lgkmcnt(6)
	v_mfma_f32_16x16x32_bf16 v[74:77], v[74:77], v[54:57], v[82:85]
	s_waitcnt lgkmcnt(4)
	v_mfma_f32_16x16x32_bf16 v[82:85], v[86:89], v[54:57], v[90:93]
	s_waitcnt lgkmcnt(1)
	v_mfma_f32_16x16x32_bf16 v[86:89], v[98:101], v[54:57], v[94:97]
	s_waitcnt lgkmcnt(0)
	v_mfma_f32_16x16x32_bf16 v[54:57], v[102:105], v[54:57], v[62:65]
	v_mul_f32_e64 v36, v36, v8
	v_mul_f32_e64 v37, v37, v8
	v_pk_mul_f32 v[32:33], v[32:33], v[8:9] op_sel_hi:[1,0]
	v_pk_mul_f32 v[62:63], v[38:39], v[8:9] op_sel_hi:[1,0]
	v_pk_mul_f32 v[34:35], v[34:35], v[8:9] op_sel_hi:[1,0]
	v_cvt_pk_bf16_f32 v32, v32, v33
	v_cvt_pk_bf16_f32 v33, v36, v37
	ds_read_b64_tr_b16 v[38:39], v133 offset:39168
	ds_read_b64_tr_b16 v[36:37], v133 offset:34816
	v_cvt_pk_bf16_f32 v34, v34, v35
	v_cvt_pk_bf16_f32 v35, v62, v63
	ds_read_b64_tr_b16 v[64:65], v133 offset:39200
	ds_read_b64_tr_b16 v[62:63], v133 offset:34848
	ds_read_b64_tr_b16 v[90:91], v133 offset:34880
	ds_read_b64_tr_b16 v[94:95], v133 offset:34912
	ds_read_b64_tr_b16 v[92:93], v133 offset:39232
	ds_read_b64_tr_b16 v[96:97], v133 offset:39264
	s_waitcnt lgkmcnt(6)
	v_mfma_f32_16x16x32_bf16 v[36:39], v[36:39], v[32:35], v[58:61]
	s_waitcnt lgkmcnt(4)
	v_mfma_f32_16x16x32_bf16 v[58:61], v[62:65], v[32:35], v[66:69]
	s_nop 2
	ds_read_b64_tr_b16 v[66:67], v133 offset:34944
	ds_read_b64_tr_b16 v[68:69], v133 offset:39296
	s_waitcnt lgkmcnt(3)
	v_mfma_f32_16x16x32_bf16 v[62:65], v[90:93], v[32:35], v[70:73]
	s_waitcnt lgkmcnt(2)
	v_mfma_f32_16x16x32_bf16 v[70:73], v[94:97], v[32:35], v[78:81]
	s_nop 2
	ds_read_b64_tr_b16 v[80:81], v133 offset:39328
	ds_read_b64_tr_b16 v[78:79], v133 offset:34976
	ds_read_b64_tr_b16 v[90:91], v133 offset:35008
	ds_read_b64_tr_b16 v[94:95], v133 offset:35040
	ds_read_b64_tr_b16 v[92:93], v133 offset:39360
	ds_read_b64_tr_b16 v[96:97], v133 offset:39392
	s_waitcnt lgkmcnt(6)
	v_mfma_f32_16x16x32_bf16 v[66:69], v[66:69], v[32:35], v[74:77]
	s_waitcnt lgkmcnt(4)
	v_mfma_f32_16x16x32_bf16 v[74:77], v[78:81], v[32:35], v[82:85]
	s_waitcnt lgkmcnt(1)
	v_mfma_f32_16x16x32_bf16 v[78:81], v[90:93], v[32:35], v[86:89]
	s_waitcnt lgkmcnt(0)
	v_mfma_f32_16x16x32_bf16 v[32:35], v[94:97], v[32:35], v[54:57]
	v_mul_f32_e64 v28, v28, v8
	v_mul_f32_e64 v29, v29, v8
	v_pk_mul_f32 v[24:25], v[24:25], v[8:9] op_sel_hi:[1,0]
	v_pk_mul_f32 v[54:55], v[30:31], v[8:9] op_sel_hi:[1,0]
	v_pk_mul_f32 v[26:27], v[26:27], v[8:9] op_sel_hi:[1,0]
	v_cvt_pk_bf16_f32 v24, v24, v25
	v_cvt_pk_bf16_f32 v25, v28, v29
	ds_read_b64_tr_b16 v[30:31], v133 offset:47872
	ds_read_b64_tr_b16 v[28:29], v133 offset:43520
	v_cvt_pk_bf16_f32 v26, v26, v27
	v_cvt_pk_bf16_f32 v27, v54, v55
	ds_read_b64_tr_b16 v[56:57], v133 offset:47904
	ds_read_b64_tr_b16 v[54:55], v133 offset:43552
	ds_read_b64_tr_b16 v[82:83], v133 offset:43584
	ds_read_b64_tr_b16 v[86:87], v133 offset:43616
	ds_read_b64_tr_b16 v[84:85], v133 offset:47936
	ds_read_b64_tr_b16 v[88:89], v133 offset:47968
	s_waitcnt lgkmcnt(6)
	v_mfma_f32_16x16x32_bf16 v[28:31], v[28:31], v[24:27], v[36:39]
	s_waitcnt lgkmcnt(4)
	v_mfma_f32_16x16x32_bf16 v[36:39], v[54:57], v[24:27], v[58:61]
	s_nop 2
	ds_read_b64_tr_b16 v[58:59], v133 offset:43648
	ds_read_b64_tr_b16 v[60:61], v133 offset:48000
	s_waitcnt lgkmcnt(3)
	v_mfma_f32_16x16x32_bf16 v[54:57], v[82:85], v[24:27], v[62:65]
	s_waitcnt lgkmcnt(2)
	v_mfma_f32_16x16x32_bf16 v[62:65], v[86:89], v[24:27], v[70:73]
	s_nop 2
	ds_read_b64_tr_b16 v[72:73], v133 offset:48032
	ds_read_b64_tr_b16 v[70:71], v133 offset:43680
	ds_read_b64_tr_b16 v[82:83], v133 offset:43712
	ds_read_b64_tr_b16 v[86:87], v133 offset:43744
	ds_read_b64_tr_b16 v[84:85], v133 offset:48064
	ds_read_b64_tr_b16 v[88:89], v133 offset:48096
	s_waitcnt lgkmcnt(6)
	v_mfma_f32_16x16x32_bf16 v[58:61], v[58:61], v[24:27], v[66:69]
	s_waitcnt lgkmcnt(4)
	v_mfma_f32_16x16x32_bf16 v[66:69], v[70:73], v[24:27], v[74:77]
	s_waitcnt lgkmcnt(1)
	v_mfma_f32_16x16x32_bf16 v[70:73], v[82:85], v[24:27], v[78:81]
	s_waitcnt lgkmcnt(0)
	v_mfma_f32_16x16x32_bf16 v[24:27], v[86:89], v[24:27], v[32:35]
	s_nop 2
	ds_read_b64_tr_b16 v[34:35], v133 offset:56576
	ds_read_b64_tr_b16 v[32:33], v133 offset:52224
	ds_read_b64_tr_b16 v[76:77], v133 offset:56608
	ds_read_b64_tr_b16 v[74:75], v133 offset:52256
	ds_read_b64_tr_b16 v[78:79], v133 offset:52288
	ds_read_b64_tr_b16 v[82:83], v133 offset:52320
	ds_read_b64_tr_b16 v[80:81], v133 offset:56640
	ds_read_b64_tr_b16 v[84:85], v133 offset:56672
	v_pk_mul_f32 v[14:15], v[14:15], v[8:9] op_sel_hi:[1,0]
	v_pk_mul_f32 v[10:11], v[10:11], v[8:9] op_sel_hi:[1,0]
	v_pk_mul_f32 v[22:23], v[22:23], v[8:9] op_sel_hi:[1,0]
	v_pk_mul_f32 v[12:13], v[12:13], v[8:9] op_sel_hi:[1,0]
	v_cvt_pk_bf16_f32 v10, v10, v11
	v_cvt_pk_bf16_f32 v11, v14, v15
	v_cvt_pk_bf16_f32 v12, v12, v13
	v_cvt_pk_bf16_f32 v13, v22, v23
	s_waitcnt lgkmcnt(6)
	s_nop 0
	v_mfma_f32_16x16x32_bf16 v[28:31], v[32:35], v[10:13], v[28:31]
	s_waitcnt lgkmcnt(4)
	v_mfma_f32_16x16x32_bf16 v[32:35], v[74:77], v[10:13], v[36:39]
	s_waitcnt lgkmcnt(1)
	v_mfma_f32_16x16x32_bf16 v[36:39], v[78:81], v[10:13], v[54:57]
	s_nop 2
	ds_read_b64_tr_b16 v[54:55], v133 offset:52352
	ds_read_b64_tr_b16 v[56:57], v133 offset:56704
	s_waitcnt lgkmcnt(2)
	v_mfma_f32_16x16x32_bf16 v[62:65], v[82:85], v[10:13], v[62:65]
	ds_read_b64_tr_b16 v[76:77], v133 offset:56736
	ds_read_b64_tr_b16 v[74:75], v133 offset:52384
	ds_read_b64_tr_b16 v[78:79], v133 offset:52416
	ds_read_b64_tr_b16 v[82:83], v133 offset:52448
	ds_read_b64_tr_b16 v[80:81], v133 offset:56768
	ds_read_b64_tr_b16 v[84:85], v133 offset:56800
	s_waitcnt lgkmcnt(6)
	v_mfma_f32_16x16x32_bf16 v[54:57], v[54:57], v[10:13], v[58:61]
	s_waitcnt lgkmcnt(4)
	v_mfma_f32_16x16x32_bf16 v[58:61], v[74:77], v[10:13], v[66:69]
	s_waitcnt lgkmcnt(1)
	v_mfma_f32_16x16x32_bf16 v[66:69], v[78:81], v[10:13], v[70:73]
	s_waitcnt lgkmcnt(0)
	v_mfma_f32_16x16x32_bf16 v[10:13], v[82:85], v[10:13], v[24:27]
	v_mul_f32_e64 v4, v4, v8
	v_mul_f32_e64 v5, v5, v8
	v_pk_mul_f32 v[0:1], v[0:1], v[8:9] op_sel_hi:[1,0]
	v_pk_mul_f32 v[14:15], v[6:7], v[8:9] op_sel_hi:[1,0]
	v_cvt_pk_bf16_f32 v0, v0, v1
	v_cvt_pk_bf16_f32 v1, v4, v5
	ds_read_b64_tr_b16 v[6:7], v133 offset:65280
	ds_read_b64_tr_b16 v[4:5], v133 offset:60928
	ds_read_b64_tr_b16 v[24:25], v133 offset:65312
	ds_read_b64_tr_b16 v[22:23], v133 offset:60960
	ds_read_b64_tr_b16 v[70:71], v133 offset:60992
	ds_read_b64_tr_b16 v[74:75], v133 offset:61024
	ds_read_b64_tr_b16 v[72:73], v133 offset:65344
	ds_read_b64_tr_b16 v[76:77], v133 offset:65376
	v_pk_mul_f32 v[2:3], v[2:3], v[8:9] op_sel_hi:[1,0]
	s_nop 0
	v_cvt_pk_bf16_f32 v2, v2, v3
	v_cvt_pk_bf16_f32 v3, v14, v15
	s_waitcnt lgkmcnt(6)
	s_nop 0
	v_mfma_f32_16x16x32_bf16 v[4:7], v[4:7], v[0:3], v[28:31]
	s_waitcnt lgkmcnt(4)
	v_mfma_f32_16x16x32_bf16 v[22:25], v[22:25], v[0:3], v[32:35]
	s_nop 0
	ds_read_b64_tr_b16 v[30:31], v133 offset:61056
	s_nop 0
	ds_read_b64_tr_b16 v[32:33], v133 offset:65408
	s_waitcnt lgkmcnt(3)
	v_mfma_f32_16x16x32_bf16 v[26:29], v[70:73], v[0:3], v[36:39]
	s_waitcnt lgkmcnt(2)
	v_mfma_f32_16x16x32_bf16 v[34:37], v[74:77], v[0:3], v[62:65]
	s_nop 2
	ds_read_b64_tr_b16 v[64:65], v133 offset:65440
	ds_read_b64_tr_b16 v[62:63], v133 offset:61088
	ds_read_b64_tr_b16 v[70:71], v133 offset:61120
	ds_read_b64_tr_b16 v[74:75], v133 offset:61152
	ds_read_b64_tr_b16 v[72:73], v133 offset:65472
	ds_read_b64_tr_b16 v[76:77], v133 offset:65504
	s_waitcnt lgkmcnt(6)
	v_mfma_f32_16x16x32_bf16 v[30:33], v[30:33], v[0:3], v[54:57]
	s_waitcnt lgkmcnt(4)
	v_mfma_f32_16x16x32_bf16 v[54:57], v[62:65], v[0:3], v[58:61]
	s_waitcnt lgkmcnt(1)
	v_mfma_f32_16x16x32_bf16 v[58:61], v[70:73], v[0:3], v[66:69]
	s_waitcnt lgkmcnt(0)
	v_mfma_f32_16x16x32_bf16 v[0:3], v[74:77], v[0:3], v[10:13]
	s_add_i32 s2, s2, -1
	v_lshl_add_u64 v[8:9], s[22:23], 0, v[18:19]
	v_cvt_pk_bf16_f32 v4, v4, v5
	v_cvt_pk_bf16_f32 v5, v6, v7
	s_nop 3
	v_cvt_pk_bf16_f32 v0, v0, v1
	v_cvt_pk_bf16_f32 v1, v2, v3
	v_lshl_add_u64 v[16:17], v[16:17], 0, s[18:19]
	v_lshl_add_u64 v[18:19], v[18:19], 0, s[24:25]
	v_lshl_add_u64 v[20:21], v[20:21], 0, s[24:25]
	s_cmp_eq_u32 s2, 0
	v_cvt_pk_bf16_f32 v6, v22, v23
	v_cvt_pk_bf16_f32 v7, v24, v25
	v_cvt_pk_bf16_f32 v10, v26, v27
	v_cvt_pk_bf16_f32 v11, v28, v29
	v_cvt_pk_bf16_f32 v12, v34, v35
	v_cvt_pk_bf16_f32 v13, v36, v37
	v_cvt_pk_bf16_f32 v14, v30, v31
	v_cvt_pk_bf16_f32 v15, v32, v33
	v_cvt_pk_bf16_f32 v22, v54, v55
	v_cvt_pk_bf16_f32 v23, v56, v57
	v_cvt_pk_bf16_f32 v24, v58, v59
	v_cvt_pk_bf16_f32 v25, v60, v61
	global_store_dwordx2 v[8:9], v[4:5], off offset:-128
	global_store_dwordx2 v[8:9], v[6:7], off offset:-96
	global_store_dwordx2 v[8:9], v[10:11], off offset:-64
	global_store_dwordx2 v[8:9], v[12:13], off offset:-32
	global_store_dwordx2 v[8:9], v[14:15], off
	global_store_dwordx2 v[8:9], v[22:23], off offset:32
	global_store_dwordx2 v[8:9], v[24:25], off offset:64
	global_store_dwordx2 v[8:9], v[0:1], off offset:96
	s_cbranch_scc0 .LBB0_1059
	s_branch .LBB0_1051
